# P2 softmax: interior-tile masks skipped for chunks c>0
# speedup vs baseline: 1.0093x; 1.0061x over previous
.LBB0_208:
	s_or_b64 exec, exec, s[0:1]
	v_readlane_b32 s0, v255, 19
	v_readlane_b32 s1, v255, 20
	s_and_b64 s[0:1], s[0:1], exec
	s_cselect_b32 s0, s96, s41
	s_lshl_b32 s0, s0, 7
	s_or_b32 s13, s0, s79
	v_add_u32_e32 v0, 0, v91
	v_or_b32_e32 v1, s13, v101
	s_waitcnt lgkmcnt(0)
	v_mad_u32_u24 v1, v1, s61, v0
	ds_read_b128 v[74:77], v1
	ds_read_b128 v[78:81], v1 offset:64
	s_and_b64 s[0:1], s[98:99], exec
	s_cselect_b32 s0, s96, s41
	s_lshl_b32 s14, s0, 7
	s_waitcnt vmcnt(11) lgkmcnt(1)
	v_mfma_f32_16x16x32_bf16 v[74:77], v[74:77], v[44:47], 0
	s_or_b32 s0, s77, s14
	v_or_b32_e32 v1, s0, v101
	s_and_b64 s[0:1], s[4:5], exec
	v_mad_u32_u24 v1, v1, s61, v0
	s_cselect_b32 s0, s96, s41
	s_waitcnt vmcnt(10) lgkmcnt(0)
	v_mfma_f32_16x16x32_bf16 v[74:77], v[78:81], v[40:43], v[74:77]
	ds_read_b128 v[78:81], v1
	ds_read_b128 v[82:85], v1 offset:64
	s_lshl_b32 s0, s0, 7
	s_or_b32 s11, s0, s36
	v_or_b32_e32 v1, s11, v101
	v_mad_u32_u24 v1, v1, s61, v0
	s_waitcnt lgkmcnt(1)
	v_mfma_f32_16x16x32_bf16 v[78:81], v[78:81], v[44:47], 0
	ds_read_b128 v[86:89], v1
	s_and_b64 s[0:1], s[26:27], exec
	s_cselect_b32 s0, s96, s41
	s_waitcnt lgkmcnt(1)
	v_mfma_f32_16x16x32_bf16 v[78:81], v[82:85], v[40:43], v[78:81]
	ds_read_b128 v[82:85], v1 offset:64
	s_lshl_b32 s12, s0, 7
	s_or_b32 s0, s72, s12
	s_waitcnt lgkmcnt(1)
	v_mfma_f32_16x16x32_bf16 v[86:89], v[86:89], v[44:47], 0
	v_or_b32_e32 v1, s0, v101
	s_and_b64 s[0:1], s[24:25], exec
	v_mad_u32_u24 v1, v1, s61, v0
	s_cselect_b32 s0, s96, s41
	s_waitcnt lgkmcnt(0)
	v_mfma_f32_16x16x32_bf16 v[82:85], v[82:85], v[40:43], v[86:89]
	s_nop 2
	ds_read_b128 v[86:89], v1
	ds_read_b128 v[106:109], v1 offset:64
	s_lshl_b32 s0, s0, 7
	s_or_b32 s9, s0, s43
	v_or_b32_e32 v1, s9, v101
	v_mad_u32_u24 v1, v1, s61, v0
	s_waitcnt lgkmcnt(1)
	v_mfma_f32_16x16x32_bf16 v[86:89], v[86:89], v[44:47], 0
	ds_read_b128 v[110:113], v1
	s_and_b64 s[0:1], s[28:29], exec
	s_cselect_b32 s0, s96, s41
	s_waitcnt lgkmcnt(1)
	v_mfma_f32_16x16x32_bf16 v[86:89], v[106:109], v[40:43], v[86:89]
	ds_read_b128 v[106:109], v1 offset:64
	s_lshl_b32 s10, s0, 7
	s_or_b32 s0, s47, s10
	s_waitcnt lgkmcnt(1)
	v_mfma_f32_16x16x32_bf16 v[110:113], v[110:113], v[44:47], 0
	v_or_b32_e32 v1, s0, v101
	s_and_b64 s[0:1], s[2:3], exec
	v_mad_u32_u24 v1, v1, s61, v0
	s_cselect_b32 s0, s96, s41
	s_waitcnt lgkmcnt(0)
	v_mfma_f32_16x16x32_bf16 v[106:109], v[106:109], v[40:43], v[110:113]
	s_nop 2
	ds_read_b128 v[110:113], v1
	ds_read_b128 v[114:117], v1 offset:64
	s_lshl_b32 s0, s0, 7
	s_or_b32 s7, s0, s49
	v_or_b32_e32 v1, s7, v101
	v_mad_u32_u24 v1, v1, s61, v0
	s_waitcnt lgkmcnt(1)
	v_mfma_f32_16x16x32_bf16 v[110:113], v[110:113], v[44:47], 0
	ds_read_b128 v[118:121], v1
	s_and_b64 s[0:1], s[30:31], exec
	s_cselect_b32 s0, s96, s41
	s_waitcnt lgkmcnt(1)
	v_mfma_f32_16x16x32_bf16 v[110:113], v[114:117], v[40:43], v[110:113]
	ds_read_b128 v[114:117], v1 offset:64
	s_lshl_b32 s8, s0, 7
	s_or_b32 s0, s76, s8
	s_waitcnt lgkmcnt(1)
	v_mfma_f32_16x16x32_bf16 v[118:121], v[118:121], v[44:47], 0
	v_or_b32_e32 v1, s0, v101
	s_and_b64 s[0:1], s[80:81], exec
	v_mad_u32_u24 v1, v1, s61, v0
	s_cselect_b32 s0, s96, s41
	s_waitcnt lgkmcnt(0)
	v_mfma_f32_16x16x32_bf16 v[114:117], v[114:117], v[40:43], v[118:121]
	s_nop 2
	ds_read_b128 v[118:121], v1
	ds_read_b128 v[122:125], v1 offset:64
	s_lshl_b32 s0, s0, 7
	s_or_b32 s6, s0, s73
	v_or_b32_e32 v1, s6, v101
	v_mad_u32_u24 v0, v1, s61, v0
	s_waitcnt lgkmcnt(1)
	v_mfma_f32_16x16x32_bf16 v[118:121], v[118:121], v[44:47], 0
	ds_read_b128 v[126:129], v0
	s_cmp_lg_u32 s54, 0
	s_cselect_b64 s[0:1], -1, 0
	s_waitcnt lgkmcnt(1)
	v_mfma_f32_16x16x32_bf16 v[118:121], v[122:125], v[40:43], v[118:121]
	ds_read_b128 v[122:125], v0 offset:64
	v_cmp_lt_i32_e32 vcc, s68, v105
	s_or_b64 s[16:17], s[0:1], vcc
	s_waitcnt lgkmcnt(1)
	v_mfma_f32_16x16x32_bf16 v[44:47], v[126:129], v[44:47], 0
	v_cmp_ge_u32_e32 vcc, v103, v101
	s_and_b64 vcc, s[16:17], vcc
	v_or_b32_e32 v0, 1, v105
	s_waitcnt lgkmcnt(0)
	v_mfma_f32_16x16x32_bf16 v[40:43], v[122:125], v[40:43], v[44:47]
	v_or_b32_e32 v1, 2, v105
	v_or_b32_e32 v2, 3, v105
	s_mov_b32 s15, 0xff800000
	v_cndmask_b32_e32 v45, v96, v74, vcc
	v_cmp_lt_i32_e32 vcc, s69, v105
	s_or_b64 s[16:17], s[0:1], vcc
	v_cmp_ge_i32_e32 vcc, v0, v90
	s_and_b64 vcc, s[16:17], vcc
	v_add_u32_e32 v44, 0x80, v90
	v_cndmask_b32_e32 v0, v96, v75, vcc
	v_cmp_lt_i32_e32 vcc, s68, v1
	s_or_b64 s[16:17], s[0:1], vcc
	v_cmp_ge_i32_e32 vcc, v1, v90
	s_and_b64 vcc, vcc, s[16:17]
	v_max3_f32 v46, v45, s15, v0
	v_cndmask_b32_e32 v1, v96, v76, vcc
	v_cmp_lt_i32_e32 vcc, s68, v2
	s_or_b64 s[16:17], s[0:1], vcc
	v_cmp_ge_i32_e32 vcc, v2, v90
	s_and_b64 vcc, vcc, s[16:17]
	v_and_b32_e32 v104, 24, v104
	v_cndmask_b32_e32 v47, v96, v77, vcc
	v_max3_f32 v2, v46, v1, v47
	s_cmp_lg_u32 s54, 0
	s_cbranch_scc0 .Lmask_slow
	v_mov_b32_e32 v74, v78
	v_mov_b32_e32 v75, v79
	v_mov_b32_e32 v76, v80
	v_mov_b32_e32 v46, v81
	v_mov_b32_e32 v78, v82
	v_mov_b32_e32 v79, v83
	v_mov_b32_e32 v80, v84
	v_max3_f32 v2, v2, v74, v75
	v_mov_b32_e32 v77, v85
	v_max3_f32 v2, v2, v76, v46
	v_mov_b32_e32 v90, v86
	v_mov_b32_e32 v91, v87
	v_max3_f32 v2, v2, v78, v79
	v_mov_b32_e32 v122, v88
	v_mov_b32_e32 v123, v89
	v_mov_b32_e32 v124, v106
	v_mov_b32_e32 v125, v107
	v_max3_f32 v2, v2, v80, v77
	v_mov_b32_e32 v126, v108
	v_mov_b32_e32 v127, v109
	v_mov_b32_e32 v128, v110
	v_mov_b32_e32 v129, v111
	v_max3_f32 v2, v2, v90, v91
	v_mov_b32_e32 v130, v112
	v_mov_b32_e32 v131, v113
	v_mov_b32_e32 v132, v114
	v_mov_b32_e32 v115, v115
	v_max3_f32 v2, v2, v122, v123
	v_mov_b32_e32 v133, v116
	v_max3_f32 v2, v2, v124, v125
	v_max3_f32 v2, v2, v126, v127
	v_mov_b32_e32 v134, v117
	v_max3_f32 v2, v2, v128, v129
	v_max3_f32 v2, v2, v130, v131
	v_mov_b32_e32 v112, v118
	v_max3_f32 v2, v2, v132, v115
	v_max3_f32 v2, v2, v133, v134
	v_mov_b32_e32 v113, v119
	v_max3_f32 v82, v2, v112, v113
	v_mov_b32_e32 v114, v120
	v_lshrrev_b32_e32 v116, 2, v101
	v_mov_b32_e32 v2, v121
	s_branch .Lmask_join
.Lmask_slow:
	v_or_b32_e32 v46, s71, v103
	v_cmp_lt_i32_e32 vcc, s68, v46
	s_or_b64 vcc, s[0:1], vcc
	v_or_b32_e32 v76, 2, v46
	v_cndmask_b32_e32 v74, v96, v78, vcc
	v_cmp_lt_i32_e32 vcc, s69, v46
	s_or_b64 vcc, s[0:1], vcc
	v_or_b32_e32 v46, 3, v46
	v_cndmask_b32_e32 v75, v96, v79, vcc
	v_cmp_lt_i32_e32 vcc, s68, v76
	s_or_b64 vcc, s[0:1], vcc
	v_or_b32_e32 v77, s74, v103
	v_cndmask_b32_e32 v76, v96, v80, vcc
	v_cmp_lt_i32_e32 vcc, s68, v46
	s_or_b64 vcc, s[0:1], vcc
	v_or_b32_e32 v80, 2, v77
	v_cndmask_b32_e32 v46, v96, v81, vcc
	v_cmp_lt_i32_e32 vcc, s68, v77
	s_or_b64 vcc, s[0:1], vcc
	v_or_b32_e32 v81, s37, v103
	v_cndmask_b32_e32 v78, v96, v82, vcc
	v_cmp_lt_i32_e32 vcc, s69, v77
	s_or_b64 vcc, s[0:1], vcc
	v_or_b32_e32 v77, 3, v77
	v_cndmask_b32_e32 v79, v96, v83, vcc
	v_cmp_lt_i32_e32 vcc, s68, v80
	s_or_b64 vcc, s[0:1], vcc
	v_or_b32_e32 v82, 2, v81
	v_cndmask_b32_e32 v80, v96, v84, vcc
	v_cmp_lt_i32_e32 vcc, s68, v77
	s_or_b64 vcc, s[0:1], vcc
	v_max3_f32 v2, v2, v74, v75
	v_cndmask_b32_e32 v77, v96, v85, vcc
	v_cmp_lt_i32_e32 vcc, s68, v81
	s_or_b64 vcc, s[0:1], vcc
	v_max3_f32 v2, v2, v76, v46
	v_cndmask_b32_e32 v90, v96, v86, vcc
	v_cmp_lt_i32_e32 vcc, s69, v81
	s_or_b64 vcc, s[0:1], vcc
	v_or_b32_e32 v81, 3, v81
	v_cndmask_b32_e32 v91, v96, v87, vcc
	v_cmp_lt_i32_e32 vcc, s68, v82
	s_or_b64 vcc, s[0:1], vcc
	v_max3_f32 v2, v2, v78, v79
	v_cndmask_b32_e32 v122, v96, v88, vcc
	v_cmp_lt_i32_e32 vcc, s68, v81
	s_or_b64 vcc, s[0:1], vcc
	v_or_b32_e32 v81, s42, v103
	v_cndmask_b32_e32 v123, v96, v89, vcc
	v_cmp_lt_i32_e32 vcc, s68, v81
	s_or_b64 vcc, s[0:1], vcc
	v_or_b32_e32 v82, 2, v81
	v_cndmask_b32_e32 v124, v96, v106, vcc
	v_cmp_lt_i32_e32 vcc, s69, v81
	s_or_b64 vcc, s[0:1], vcc
	v_or_b32_e32 v81, 3, v81
	v_cndmask_b32_e32 v125, v96, v107, vcc
	v_cmp_lt_i32_e32 vcc, s68, v82
	s_or_b64 vcc, s[0:1], vcc
	v_max3_f32 v2, v2, v80, v77
	v_cndmask_b32_e32 v126, v96, v108, vcc
	v_cmp_lt_i32_e32 vcc, s68, v81
	s_or_b64 vcc, s[0:1], vcc
	v_or_b32_e32 v81, s46, v103
	v_cndmask_b32_e32 v127, v96, v109, vcc
	v_cmp_lt_i32_e32 vcc, s68, v81
	s_or_b64 vcc, s[0:1], vcc
	v_or_b32_e32 v82, 2, v81
	v_cndmask_b32_e32 v128, v96, v110, vcc
	v_cmp_lt_i32_e32 vcc, s69, v81
	s_or_b64 vcc, s[0:1], vcc
	v_or_b32_e32 v81, 3, v81
	v_cndmask_b32_e32 v129, v96, v111, vcc
	v_cmp_lt_i32_e32 vcc, s68, v82
	s_or_b64 vcc, s[0:1], vcc
	v_max3_f32 v2, v2, v90, v91
	v_cndmask_b32_e32 v130, v96, v112, vcc
	v_cmp_lt_i32_e32 vcc, s68, v81
	s_or_b64 vcc, s[0:1], vcc
	v_or_b32_e32 v81, s48, v103
	v_cndmask_b32_e32 v131, v96, v113, vcc
	v_cmp_lt_i32_e32 vcc, s68, v81
	s_or_b64 vcc, s[0:1], vcc
	v_or_b32_e32 v82, 2, v81
	v_cndmask_b32_e32 v132, v96, v114, vcc
	v_cmp_lt_i32_e32 vcc, s69, v81
	s_or_b64 vcc, s[0:1], vcc
	v_or_b32_e32 v81, 3, v81
	v_cndmask_b32_e32 v115, v96, v115, vcc
	v_cmp_lt_i32_e32 vcc, s68, v82
	s_or_b64 vcc, s[0:1], vcc
	v_max3_f32 v2, v2, v122, v123
	v_cndmask_b32_e32 v133, v96, v116, vcc
	v_cmp_lt_i32_e32 vcc, s68, v81
	v_max3_f32 v2, v2, v124, v125
	s_or_b64 vcc, s[0:1], vcc
	v_or_b32_e32 v81, s62, v103
	v_max3_f32 v2, v2, v126, v127
	v_cndmask_b32_e32 v134, v96, v117, vcc
	v_cmp_lt_i32_e32 vcc, s68, v81
	v_max3_f32 v2, v2, v128, v129
	s_or_b64 vcc, s[0:1], vcc
	v_max3_f32 v2, v2, v130, v131
	v_cndmask_b32_e32 v112, v96, v118, vcc
	v_cmp_lt_i32_e32 vcc, s69, v81
	v_max3_f32 v2, v2, v132, v115
	s_or_b64 vcc, s[0:1], vcc
	v_max3_f32 v2, v2, v133, v134
	v_cndmask_b32_e32 v113, v96, v119, vcc
	v_max3_f32 v82, v2, v112, v113
	v_or_b32_e32 v2, 2, v81
	v_cmp_lt_i32_e32 vcc, s68, v2
	s_or_b64 vcc, s[0:1], vcc
	v_or_b32_e32 v2, 3, v81
	v_cndmask_b32_e32 v114, v96, v120, vcc
	v_cmp_lt_i32_e32 vcc, s68, v2
	s_or_b64 vcc, s[0:1], vcc
	v_lshrrev_b32_e32 v116, 2, v101
	v_cndmask_b32_e32 v2, v96, v121, vcc
.Lmask_join:
	v_max3_f32 v81, v82, v114, v2
	v_or_b32_e32 v82, s67, v103
	v_cmp_lt_i32_e32 vcc, s68, v82
	s_or_b64 s[16:17], s[0:1], vcc
	v_cmp_le_i32_e32 vcc, v82, v44
	s_and_b64 vcc, s[16:17], vcc
	v_or_b32_e32 v116, v103, v116
	v_cndmask_b32_e32 v108, v96, v40, vcc
	v_cmp_lt_i32_e32 vcc, s69, v82
	s_or_b64 s[16:17], s[0:1], vcc
	v_cmp_lt_i32_e32 vcc, v82, v44
	s_and_b64 vcc, s[16:17], vcc
	v_mul_u32_u24_e32 v116, 0x90, v116
	v_cndmask_b32_e32 v109, v96, v41, vcc
	v_or_b32_e32 v41, 2, v82
	v_cmp_lt_i32_e32 vcc, s68, v41
	s_or_b64 s[16:17], s[0:1], vcc
	v_cmp_le_i32_e32 vcc, v41, v44
	s_and_b64 vcc, s[16:17], vcc
	v_or_b32_e32 v41, 3, v82
	v_cndmask_b32_e32 v110, v96, v42, vcc
	v_cmp_lt_i32_e32 vcc, s68, v41
	s_or_b64 s[0:1], s[0:1], vcc
	v_cmp_le_i32_e32 vcc, v41, v44
	v_and_b32_e32 v42, 64, v95
	s_and_b64 vcc, s[0:1], vcc
	v_xor_b32_e32 v41, 16, v95
	v_add_u32_e32 v42, 64, v42
	v_cndmask_b32_e32 v111, v96, v43, vcc
	v_cmp_lt_i32_e32 vcc, v41, v42
	v_max3_f32 v40, v81, v108, v109
	v_max3_f32 v40, v40, v110, v111
	v_cndmask_b32_e32 v41, v95, v41, vcc
	v_lshlrev_b32_e32 v105, 2, v41
	ds_bpermute_b32 v41, v105, v40
	s_or_b32 s0, s14, s50
	v_add3_u32 v104, 0, v116, v104
	s_mulk_i32 s13, 0x90
	s_mulk_i32 s0, 0x90
	s_waitcnt lgkmcnt(0)
	v_max_f32_e32 v41, v41, v41
	v_max_f32_e32 v40, v40, v41
	v_xor_b32_e32 v41, 32, v95
	v_cmp_lt_i32_e32 vcc, v41, v42
	s_mulk_i32 s11, 0x90
	s_mulk_i32 s9, 0x90
	v_cndmask_b32_e32 v41, v95, v41, vcc
	v_lshlrev_b32_e32 v106, 2, v41
	ds_bpermute_b32 v41, v106, v40
	s_mulk_i32 s7, 0x90
	s_mulk_i32 s6, 0x90
	s_waitcnt lgkmcnt(0)
	v_max_f32_e32 v41, v41, v41
	v_max_f32_e32 v40, v40, v41
	v_mul_f32_e32 v40, 0x3e38aa3b, v40
	v_max_f32_e32 v41, v53, v53
	v_max_f32_e32 v107, v40, v41
	v_fma_f32 v42, v74, s70, -v107
	v_fma_f32 v1, v1, s70, -v107
	v_exp_f32_e32 v82, v42
	v_fma_f32 v42, v75, s70, -v107
	v_exp_f32_e32 v88, v1
	v_fma_f32 v1, v47, s70, -v107
	v_exp_f32_e32 v83, v42
	v_fma_f32 v42, v76, s70, -v107
	v_exp_f32_e32 v89, v1
	v_exp_f32_e32 v84, v42
	v_fma_f32 v42, v46, s70, -v107
	v_fma_f32 v43, v80, s70, -v107
	v_exp_f32_e32 v85, v42
	v_exp_f32_e32 v80, v43
	v_fma_f32 v43, v77, s70, -v107
	v_exp_f32_e32 v81, v43
	v_fma_f32 v0, v0, s70, -v107
	v_exp_f32_e32 v87, v0
	v_pk_add_f32 v[0:1], v[88:89], 0 op_sel_hi:[1,0]
	v_fma_f32 v42, v78, s70, -v107
	v_exp_f32_e32 v74, v42
	v_fma_f32 v42, v79, s70, -v107
	v_pk_add_f32 v[0:1], v[84:85], v[0:1]
	v_exp_f32_e32 v75, v42
	v_pk_add_f32 v[42:43], v[80:81], v[0:1]
	v_fma_f32 v0, v90, s70, -v107
	v_exp_f32_e32 v76, v0
	v_fma_f32 v0, v91, s70, -v107
	v_exp_f32_e32 v77, v0
	v_fma_f32 v0, v122, s70, -v107
	v_exp_f32_e32 v78, v0
	v_fma_f32 v0, v123, s70, -v107
	v_fma_f32 v40, v45, s70, -v107
	v_exp_f32_e32 v79, v0
	v_fma_f32 v44, v126, s70, -v107
	v_fma_f32 v45, v127, s70, -v107
	v_exp_f32_e32 v44, v44
	v_exp_f32_e32 v45, v45
	v_exp_f32_e32 v86, v40
	v_pk_add_f32 v[42:43], v[78:79], v[42:43]
	v_fma_f32 v0, v124, s70, -v107
	v_fma_f32 v1, v125, s70, -v107
	v_pk_add_f32 v[46:47], v[44:45], v[42:43]
	v_fma_f32 v42, v130, s70, -v107
	v_add_u32_e32 v126, s13, v104
	v_add_u32_e32 v130, s0, v104
	v_pk_add_f32 v[40:41], v[86:87], 0 op_sel_hi:[1,0]
	v_exp_f32_e32 v0, v0
	v_exp_f32_e32 v1, v1
	ds_read_b64_tr_b16 v[116:117], v126 offset:36864
	ds_read_b64_tr_b16 v[118:119], v130 offset:36864
	v_pk_add_f32 v[40:41], v[82:83], v[40:41]
	v_fma_f32 v43, v131, s70, -v107
	v_pk_add_f32 v[40:41], v[74:75], v[40:41]
	s_or_b32 s0, s12, s51
	v_pk_add_f32 v[40:41], v[76:77], v[40:41]
	s_mulk_i32 s0, 0x90
	v_pk_add_f32 v[90:91], v[0:1], v[40:41]
	v_fma_f32 v40, v128, s70, -v107
	v_fma_f32 v41, v129, s70, -v107
	ds_read_b64_tr_b16 v[122:123], v130 offset:36896
	ds_read_b64_tr_b16 v[120:121], v126 offset:36896
	ds_read_b64_tr_b16 v[124:125], v126 offset:36928
	ds_read_b64_tr_b16 v[128:129], v126 offset:36960
	ds_read_b64_tr_b16 v[126:127], v130 offset:36928
	ds_read_b64_tr_b16 v[130:131], v130 offset:36960
	v_cvt_pk_bf16_f32 v86, v86, v87
	v_cvt_pk_bf16_f32 v87, v88, v89
	v_cvt_pk_bf16_f32 v88, v82, v83
	v_cvt_pk_bf16_f32 v89, v84, v85
	v_fma_f32 v83, v115, s70, -v107
	v_add_u32_e32 v115, s11, v104
	v_add_u32_e32 v138, s0, v104
	s_waitcnt lgkmcnt(6)
	v_mfma_f32_16x16x32_bf16 v[116:119], v[116:119], v[86:89], 0
	v_fma_f32 v82, v132, s70, -v107
	v_fma_f32 v84, v133, s70, -v107
	v_fma_f32 v85, v134, s70, -v107
	s_waitcnt lgkmcnt(4)
	v_mfma_f32_16x16x32_bf16 v[120:123], v[120:123], v[86:89], 0
	v_cvt_pk_bf16_f32 v74, v74, v75
	v_cvt_pk_bf16_f32 v75, v80, v81
	v_cvt_pk_bf16_f32 v76, v76, v77
	s_waitcnt lgkmcnt(1)
	v_mfma_f32_16x16x32_bf16 v[124:127], v[124:127], v[86:89], 0
	v_cvt_pk_bf16_f32 v77, v78, v79
	v_fma_f32 v112, v112, s70, -v107
	s_or_b32 s0, s10, s33
	s_waitcnt lgkmcnt(0)
	v_mfma_f32_16x16x32_bf16 v[86:89], v[128:131], v[86:89], 0
	ds_read_b64_tr_b16 v[128:129], v115 offset:36864
	ds_read_b64_tr_b16 v[130:131], v138 offset:36864
	ds_read_b64_tr_b16 v[80:81], v138 offset:36896
	ds_read_b64_tr_b16 v[78:79], v115 offset:36896
	ds_read_b64_tr_b16 v[132:133], v115 offset:36928
	ds_read_b64_tr_b16 v[136:137], v115 offset:36960
	ds_read_b64_tr_b16 v[134:135], v138 offset:36928
	ds_read_b64_tr_b16 v[138:139], v138 offset:36960
	v_exp_f32_e32 v140, v112
	v_fma_f32 v112, v113, s70, -v107
	s_mulk_i32 s0, 0x90
	s_waitcnt lgkmcnt(6)
	v_mfma_f32_16x16x32_bf16 v[116:119], v[128:131], v[74:77], v[116:119]
	v_exp_f32_e32 v141, v112
	v_fma_f32 v112, v114, s70, -v107
	v_exp_f32_e32 v40, v40
	s_waitcnt lgkmcnt(4)
	v_mfma_f32_16x16x32_bf16 v[78:81], v[78:81], v[74:77], v[120:123]
	v_exp_f32_e32 v41, v41
	v_exp_f32_e32 v42, v42
	v_exp_f32_e32 v43, v43
	s_waitcnt lgkmcnt(1)
	v_mfma_f32_16x16x32_bf16 v[120:123], v[132:135], v[74:77], v[124:127]
	v_exp_f32_e32 v132, v112
	v_exp_f32_e32 v82, v82
	v_exp_f32_e32 v83, v83
	s_waitcnt lgkmcnt(0)
	v_mfma_f32_16x16x32_bf16 v[74:77], v[136:139], v[74:77], v[86:89]
	v_add_f32_e64 v90, v40, v90
	v_add_f32_e64 v91, v41, v91
	v_pk_add_f32 v[46:47], v[42:43], v[46:47]
	v_exp_f32_e32 v84, v84
	v_cvt_pk_bf16_f32 v86, v0, v1
	v_add_u32_e32 v0, s9, v104
	v_add_u32_e32 v1, s0, v104
	ds_read_b64_tr_b16 v[112:113], v0 offset:36864
	ds_read_b64_tr_b16 v[114:115], v1 offset:36864
	v_cvt_pk_bf16_f32 v88, v40, v41
	v_cvt_pk_bf16_f32 v89, v42, v43
	ds_read_b64_tr_b16 v[42:43], v1 offset:36896
	ds_read_b64_tr_b16 v[40:41], v0 offset:36896
	ds_read_b64_tr_b16 v[124:125], v0 offset:36928
	ds_read_b64_tr_b16 v[128:129], v0 offset:36960
	ds_read_b64_tr_b16 v[126:127], v1 offset:36928
	ds_read_b64_tr_b16 v[130:131], v1 offset:36960
	s_or_b32 s0, s8, s35
	v_exp_f32_e32 v85, v85
	v_pk_add_f32 v[90:91], v[82:83], v[90:91]
	v_cvt_pk_bf16_f32 v87, v44, v45
	v_fma_f32 v0, v2, s70, -v107
	v_fma_f32 v2, v108, s70, -v107
	v_fma_f32 v44, v110, s70, -v107
	s_mulk_i32 s0, 0x90
	v_exp_f32_e32 v133, v0
	v_pk_add_f32 v[0:1], v[140:141], v[90:91]
	s_waitcnt lgkmcnt(4)
	v_mfma_f32_16x16x32_bf16 v[40:43], v[40:43], v[86:89], v[78:81]
	v_exp_f32_e32 v90, v2
	v_fma_f32 v2, v109, s70, -v107
	v_add_u32_e32 v45, s7, v104
	s_waitcnt lgkmcnt(1)
	v_mfma_f32_16x16x32_bf16 v[78:81], v[124:127], v[86:89], v[120:123]
	v_exp_f32_e32 v124, v44
	v_fma_f32 v44, v111, s70, -v107
	v_add_u32_e32 v91, s0, v104
	v_mfma_f32_16x16x32_bf16 v[112:115], v[112:115], v[86:89], v[116:119]
	v_exp_f32_e32 v125, v44
	v_pk_add_f32 v[46:47], v[84:85], v[46:47]
	s_and_b64 s[0:1], s[52:53], exec
	s_waitcnt lgkmcnt(0)
	v_mfma_f32_16x16x32_bf16 v[74:77], v[128:131], v[86:89], v[74:77]
	ds_read_b64_tr_b16 v[86:87], v45 offset:36864
	ds_read_b64_tr_b16 v[88:89], v91 offset:36864
	ds_read_b64_tr_b16 v[110:111], v91 offset:36896
	ds_read_b64_tr_b16 v[108:109], v45 offset:36896
	ds_read_b64_tr_b16 v[116:117], v45 offset:36928
	ds_read_b64_tr_b16 v[120:121], v45 offset:36960
	ds_read_b64_tr_b16 v[118:119], v91 offset:36928
	ds_read_b64_tr_b16 v[122:123], v91 offset:36960
	v_exp_f32_e32 v91, v2
	v_cvt_pk_bf16_f32 v82, v82, v83
	v_cvt_pk_bf16_f32 v83, v84, v85
	v_cvt_pk_bf16_f32 v84, v140, v141
	v_cvt_pk_bf16_f32 v85, v132, v133
	v_pk_add_f32 v[44:45], v[132:133], v[46:47]
	s_cselect_b32 s0, s96, s41
	s_waitcnt lgkmcnt(4)
	v_mfma_f32_16x16x32_bf16 v[40:43], v[108:111], v[82:85], v[40:43]
	v_add_f32_e64 v108, v124, v44
	v_add_f32_e64 v109, v125, v45
	v_pk_add_f32 v[0:1], v[90:91], v[0:1]
	s_lshl_b32 s0, s0, 7
	v_pk_mov_b32 v[110:111], v[0:1], v[108:109] op_sel:[1,0]
	v_mov_b32_e32 v1, v109
	s_or_b32 s0, s0, s75
	v_pk_add_f32 v[0:1], v[110:111], v[0:1]
	s_mulk_i32 s0, 0x90
	s_waitcnt lgkmcnt(1)
	v_mfma_f32_16x16x32_bf16 v[44:47], v[116:119], v[82:85], v[78:81]
	v_add_f32_e32 v116, v0, v1
	v_cvt_pk_bf16_f32 v0, v90, v91
	v_add_u32_e32 v90, s6, v104
	v_add_u32_e32 v91, s0, v104
	ds_read_b64_tr_b16 v[78:79], v90 offset:36864
	ds_read_b64_tr_b16 v[80:81], v91 offset:36864
	v_mfma_f32_16x16x32_bf16 v[86:89], v[86:89], v[82:85], v[112:115]
	v_cvt_pk_bf16_f32 v1, v124, v125
	v_mov_b32_e32 v2, v3
	s_waitcnt vmcnt(0)
	v_permlane16_swap_b32_e32 v238, v240
	v_permlane16_swap_b32_e32 v239, v241
	v_permlane16_swap_b32_e32 v242, v244
	v_permlane16_swap_b32_e32 v243, v245
	v_permlane16_swap_b32_e32 v246, v248
	v_permlane16_swap_b32_e32 v247, v249
	v_permlane16_swap_b32_e32 v250, v252
	v_permlane16_swap_b32_e32 v251, v253
	v_permlane16_swap_b32_e32 v154, v156
	v_permlane16_swap_b32_e32 v155, v157
	v_permlane16_swap_b32_e32 v216, v218
	v_permlane16_swap_b32_e32 v217, v219
	v_mov_b64_e32 v[68:69], v[238:239]
	v_mov_b64_e32 v[62:63], v[240:241]
	v_mov_b64_e32 v[56:57], v[242:243]
	v_mov_b64_e32 v[48:49], v[244:245]
	v_mov_b64_e32 v[70:71], v[246:247]
	v_mov_b64_e32 v[64:65], v[248:249]
	v_mov_b64_e32 v[58:59], v[250:251]
	v_mov_b64_e32 v[50:51], v[252:253]
	v_mov_b64_e32 v[72:73], v[154:155]
	v_mov_b64_e32 v[66:67], v[156:157]
	v_mov_b64_e32 v[60:61], v[216:217]
	v_mov_b64_e32 v[54:55], v[218:219]
	v_and_b32_e32 v104, 0xffff0000, v70
	s_waitcnt lgkmcnt(2)
	v_mfma_f32_16x16x32_bf16 v[74:77], v[120:123], v[82:85], v[74:77]
	ds_read_b64_tr_b16 v[84:85], v91 offset:36896
	ds_read_b64_tr_b16 v[82:83], v90 offset:36896
	ds_read_b64_tr_b16 v[108:109], v90 offset:36928
	ds_read_b64_tr_b16 v[112:113], v90 offset:36960
	ds_read_b64_tr_b16 v[110:111], v91 offset:36928
	ds_read_b64_tr_b16 v[114:115], v91 offset:36960
	v_lshlrev_b32_e32 v90, 16, v70
	v_mul_f32_e32 v90, 0xbfb8aa3b, v90
	s_waitcnt lgkmcnt(6)
	v_mfma_f32_16x16x32_bf16 v[78:81], v[78:81], v[0:3], v[86:89]
	v_exp_f32_e32 v90, v90
	s_add_i32 s40, s40, 1
	s_nop 0
	ds_bpermute_b32 v86, v105, v116
	s_waitcnt lgkmcnt(5)
	v_mfma_f32_16x16x32_bf16 v[82:85], v[82:85], v[0:3], v[40:43]
	v_lshlrev_b32_e32 v88, 16, v73
	v_and_b32_e32 v89, 0xffff0000, v73
	v_lshlrev_b32_e32 v105, 16, v71
	s_waitcnt lgkmcnt(0)
	v_add_f32_e32 v40, v116, v86
	ds_bpermute_b32 v41, v106, v40
	v_sub_f32_e32 v42, v53, v107
	v_exp_f32_e32 v42, v42
	v_mfma_f32_16x16x32_bf16 v[44:47], v[108:111], v[0:3], v[44:47]
	v_and_b32_e32 v106, 0xffff0000, v69
	s_waitcnt lgkmcnt(0)
	v_add_f32_e32 v40, v40, v41
	v_add_f32_e32 v86, v42, v40
	v_mfma_f32_16x16x32_bf16 v[40:43], v[112:115], v[0:3], v[74:77]
	v_lshl_add_u32 v1, v103, 2, v102
	v_lshlrev_b32_e32 v2, 16, v68
	v_lshlrev_b32_e32 v102, 16, v69
	v_add_u32_e32 v74, s38, v101
	s_mov_b32 s100, 0x9f57000
	v_lshl_add_u64 v[22:23], v[20:21], 0, s[100:101]
	global_load_dwordx4 v[28:31], v[22:23], off offset:3072
	v_and_b32_e32 v101, 0xffff0000, v68
	v_lshlrev_b32_e32 v68, 16, v72
	v_and_b32_e32 v69, 0xffff0000, v72
	v_pk_mul_f32 v[72:73], v[68:69], v[68:69]
	v_mul_f32_e32 v2, 0xbfb8aa3b, v2
	v_fmamk_f32 v72, v72, 0xbdd2d3e7, v93
	v_mul_f32_e32 v72, v72, v68
	v_exp_f32_e32 v2, v2
	v_exp_f32_e32 v91, v72
	v_mul_f32_e32 v72, 0xbfb8aa3b, v101
	v_fmamk_f32 v73, v73, 0xbdd2d3e7, v93
	v_and_b32_e32 v107, 0xffff0000, v71
	v_pk_mul_f32 v[70:71], v[88:89], v[88:89]
	v_exp_f32_e32 v101, v72
	v_mul_f32_e32 v72, 0xbfb8aa3b, v104
	v_mul_f32_e32 v73, v73, v69
	v_exp_f32_e32 v72, v72
	v_exp_f32_e32 v73, v73
	v_fmamk_f32 v70, v70, 0xbdd2d3e7, v93
	v_mul_f32_e32 v102, 0xbfb8aa3b, v102
	v_mul_f32_e32 v104, 0xbfb8aa3b, v105
	v_mul_f32_e32 v70, v70, v88
	v_exp_f32_e32 v102, v102
	v_exp_f32_e32 v104, v104
	v_exp_f32_e32 v105, v70
	v_mul_f32_e32 v70, 0xbfb8aa3b, v106
	v_fmamk_f32 v71, v71, 0xbdd2d3e7, v93
	v_add_f32_e32 v2, 1.0, v2
	v_pk_add_f32 v[90:91], v[90:91], 1.0 op_sel_hi:[1,0]
	v_exp_f32_e32 v109, v70
	v_mul_f32_e32 v70, 0xbfb8aa3b, v107
	v_mul_f32_e32 v71, v71, v89
	v_rcp_f32_e32 v106, v2
	v_mul_f32_e32 v2, v90, v91
	v_exp_f32_e32 v70, v70
	v_exp_f32_e32 v71, v71
	v_rcp_f32_e32 v90, v2
	v_add_f32_e32 v2, 1.0, v101
	v_pk_add_f32 v[72:73], v[72:73], 1.0 op_sel_hi:[1,0]
	v_rcp_f32_e32 v107, v2
	v_mul_f32_e32 v2, v72, v73
	v_ashrrev_i32_e32 v75, 31, v74
	v_rcp_f32_e32 v91, v2
	v_add_f32_e32 v2, 1.0, v102
	v_pk_add_f32 v[72:73], v[104:105], 1.0 op_sel_hi:[1,0]
	v_lshlrev_b64 v[74:75], 11, v[74:75]
	v_rcp_f32_e32 v108, v2
	v_mul_f32_e32 v2, v72, v73
	v_rcp_f32_e32 v0, v86
	v_lshl_add_u64 v[86:87], s[44:45], 0, v[74:75]
	ds_read_b128 v[74:77], v1
	v_rcp_f32_e32 v104, v2
	v_add_f32_e32 v2, 1.0, v109
	v_pk_add_f32 v[70:71], v[70:71], 1.0 op_sel_hi:[1,0]
	v_rcp_f32_e32 v109, v2
	v_mul_f32_e32 v2, v70, v71
	v_rcp_f32_e32 v105, v2
	ds_read_b128 v[70:73], v1 offset:64
	s_waitcnt lgkmcnt(1)
	v_pk_mul_f32 v[76:77], v[76:77], v[88:89]
	v_pk_mul_f32 v[68:69], v[74:75], v[68:69]
	v_pk_mul_f32 v[80:81], v[0:1], v[80:81] op_sel_hi:[0,1]
	v_pk_mul_f32 v[78:79], v[0:1], v[78:79] op_sel_hi:[0,1]
	v_pk_mul_f32 v[68:69], v[90:91], v[68:69]
	v_pk_mul_f32 v[74:75], v[104:105], v[76:77]
	v_pk_fma_f32 v[68:69], v[106:107], v[78:79], v[68:69]
	v_pk_fma_f32 v[74:75], v[108:109], v[80:81], v[74:75]
	v_lshlrev_b32_e32 v2, 1, v103
	v_cvt_pk_bf16_f32 v76, v68, v69
	v_cvt_pk_bf16_f32 v77, v74, v75
	v_lshl_add_u64 v[68:69], v[86:87], 0, v[2:3]
	v_bfe_u32 v158, v52, 4, 1
	v_mul_u32_u24_e32 v158, 24, v158
	v_mov_b32_e32 v159, 0
	v_lshl_add_u64 v[158:159], v[68:69], 0, v[158:159]
	v_mov_b64_e32 v[238:239], v[76:77]
	v_pk_mul_f32 v[74:75], v[0:1], v[84:85] op_sel_hi:[0,1]
	v_pk_mul_f32 v[76:77], v[0:1], v[82:83] op_sel_hi:[0,1]
	v_lshlrev_b32_e32 v2, 16, v62
	v_and_b32_e32 v82, 0xffff0000, v62
	v_lshlrev_b32_e32 v83, 16, v63
	v_and_b32_e32 v84, 0xffff0000, v63
	v_lshlrev_b32_e32 v62, 16, v66
	v_and_b32_e32 v63, 0xffff0000, v66
	v_pk_mul_f32 v[78:79], v[62:63], v[62:63]
	v_lshlrev_b32_e32 v80, 16, v64
	v_fmamk_f32 v78, v78, 0xbdd2d3e7, v93
	v_mul_f32_e32 v2, 0xbfb8aa3b, v2
	v_mul_f32_e32 v80, 0xbfb8aa3b, v80
	v_mul_f32_e32 v78, v78, v62
	v_and_b32_e32 v85, 0xffff0000, v64
	v_lshlrev_b32_e32 v86, 16, v65
	v_and_b32_e32 v87, 0xffff0000, v65
	s_mov_b32 s100, 0x9f5a000
	v_lshl_add_u64 v[24:25], v[20:21], 0, s[100:101]
	global_load_dwordx4 v[24:27], v[24:25], off offset:2048
	v_lshlrev_b32_e32 v64, 16, v67
	v_and_b32_e32 v65, 0xffff0000, v67
	v_exp_f32_e32 v2, v2
	v_exp_f32_e32 v80, v80
	v_exp_f32_e32 v81, v78
	v_mul_f32_e32 v78, 0xbfb8aa3b, v82
	v_fmamk_f32 v79, v79, 0xbdd2d3e7, v93
	v_pk_mul_f32 v[66:67], v[64:65], v[64:65]
	v_exp_f32_e32 v88, v78
	v_mul_f32_e32 v78, 0xbfb8aa3b, v85
	v_mul_f32_e32 v79, v79, v63
	v_exp_f32_e32 v78, v78
	v_exp_f32_e32 v79, v79
	v_mul_f32_e32 v82, 0xbfb8aa3b, v83
	v_fmamk_f32 v66, v66, 0xbdd2d3e7, v93
	v_exp_f32_e32 v89, v82
	v_mul_f32_e32 v82, 0xbfb8aa3b, v86
	v_mul_f32_e32 v66, v66, v64
	v_exp_f32_e32 v82, v82
	v_exp_f32_e32 v83, v66
	v_mul_f32_e32 v66, 0xbfb8aa3b, v84
	v_fmamk_f32 v67, v67, 0xbdd2d3e7, v93
	v_add_f32_e32 v2, 1.0, v2
	v_pk_add_f32 v[80:81], v[80:81], 1.0 op_sel_hi:[1,0]
	v_exp_f32_e32 v86, v66
	v_mul_f32_e32 v66, 0xbfb8aa3b, v87
	v_mul_f32_e32 v67, v67, v65
	v_rcp_f32_e32 v84, v2
	v_mul_f32_e32 v2, v80, v81
	v_exp_f32_e32 v66, v66
	v_exp_f32_e32 v67, v67
	v_rcp_f32_e32 v80, v2
	v_add_f32_e32 v2, 1.0, v88
	v_pk_add_f32 v[78:79], v[78:79], 1.0 op_sel_hi:[1,0]
	v_rcp_f32_e32 v85, v2
	v_mul_f32_e32 v2, v78, v79
	v_rcp_f32_e32 v81, v2
	v_add_f32_e32 v2, 1.0, v89
	v_pk_add_f32 v[82:83], v[82:83], 1.0 op_sel_hi:[1,0]
	v_rcp_f32_e32 v78, v2
	v_mul_f32_e32 v2, v82, v83
	v_rcp_f32_e32 v82, v2
	v_add_f32_e32 v2, 1.0, v86
	v_pk_add_f32 v[66:67], v[66:67], 1.0 op_sel_hi:[1,0]
	v_rcp_f32_e32 v79, v2
	v_mul_f32_e32 v2, v66, v67
	v_rcp_f32_e32 v83, v2
	s_waitcnt lgkmcnt(0)
	v_pk_mul_f32 v[64:65], v[72:73], v[64:65]
	v_lshlrev_b32_e32 v2, 16, v56
	v_and_b32_e32 v72, 0xffff0000, v56
	v_pk_mul_f32 v[64:65], v[82:83], v[64:65]
	v_lshlrev_b32_e32 v73, 16, v57
	v_pk_fma_f32 v[64:65], v[78:79], v[74:75], v[64:65]
	v_and_b32_e32 v74, 0xffff0000, v57
	v_lshlrev_b32_e32 v56, 16, v60
	v_and_b32_e32 v57, 0xffff0000, v60
	v_pk_mul_f32 v[66:67], v[0:1], v[46:47] op_sel_hi:[0,1]
	v_pk_mul_f32 v[46:47], v[56:57], v[56:57]
	v_pk_mul_f32 v[62:63], v[70:71], v[62:63]
	v_lshlrev_b32_e32 v75, 16, v58
	v_fmamk_f32 v46, v46, 0xbdd2d3e7, v93
	v_pk_mul_f32 v[62:63], v[80:81], v[62:63]
	v_mul_f32_e32 v2, 0xbfb8aa3b, v2
	v_mul_f32_e32 v60, 0xbfb8aa3b, v75
	v_mul_f32_e32 v46, v46, v56
	v_pk_fma_f32 v[62:63], v[84:85], v[76:77], v[62:63]
	v_and_b32_e32 v76, 0xffff0000, v58
	v_lshlrev_b32_e32 v77, 16, v59
	v_and_b32_e32 v78, 0xffff0000, v59
	v_lshlrev_b32_e32 v58, 16, v61
	v_and_b32_e32 v59, 0xffff0000, v61
	v_exp_f32_e32 v2, v2
	v_exp_f32_e32 v60, v60
	s_mov_b32 s100, 0x9f5d000
	v_lshl_add_u64 v[22:23], v[20:21], 0, s[100:101]
	global_load_dwordx4 v[36:39], v[22:23], off offset:1024
	v_exp_f32_e32 v61, v46
	v_mul_f32_e32 v46, 0xbfb8aa3b, v72
	v_fmamk_f32 v47, v47, 0xbdd2d3e7, v93
	v_pk_mul_f32 v[70:71], v[0:1], v[44:45] op_sel_hi:[0,1]
	v_pk_mul_f32 v[44:45], v[58:59], v[58:59]
	v_exp_f32_e32 v75, v46
	v_mul_f32_e32 v46, 0xbfb8aa3b, v76
	v_mul_f32_e32 v47, v47, v57
	v_exp_f32_e32 v46, v46
	v_exp_f32_e32 v47, v47
	v_mul_f32_e32 v72, 0xbfb8aa3b, v73
	v_fmamk_f32 v44, v44, 0xbdd2d3e7, v93
	v_exp_f32_e32 v76, v72
	v_mul_f32_e32 v72, 0xbfb8aa3b, v77
	v_mul_f32_e32 v44, v44, v58
	v_exp_f32_e32 v72, v72
	v_exp_f32_e32 v73, v44
	v_mul_f32_e32 v44, 0xbfb8aa3b, v74
	v_fmamk_f32 v45, v45, 0xbdd2d3e7, v93
	v_add_f32_e32 v2, 1.0, v2
	v_pk_add_f32 v[60:61], v[60:61], 1.0 op_sel_hi:[1,0]
	v_exp_f32_e32 v77, v44
	v_mul_f32_e32 v44, 0xbfb8aa3b, v78
	v_mul_f32_e32 v45, v45, v59
	v_rcp_f32_e32 v74, v2
	v_mul_f32_e32 v2, v60, v61
	v_exp_f32_e32 v44, v44
	v_exp_f32_e32 v45, v45
	v_rcp_f32_e32 v60, v2
	v_add_f32_e32 v2, 1.0, v75
	v_pk_add_f32 v[46:47], v[46:47], 1.0 op_sel_hi:[1,0]
	v_rcp_f32_e32 v75, v2
	v_mul_f32_e32 v2, v46, v47
	v_rcp_f32_e32 v61, v2
	v_add_f32_e32 v2, 1.0, v76
	v_pk_add_f32 v[46:47], v[72:73], 1.0 op_sel_hi:[1,0]
	v_cvt_pk_bf16_f32 v62, v62, v63
	v_cvt_pk_bf16_f32 v63, v64, v65
	v_rcp_f32_e32 v76, v2
	v_mul_f32_e32 v2, v46, v47
	v_mov_b64_e32 v[240:241], v[62:63]
	s_nop 1
	v_permlane16_swap_b32_e32 v238, v240
	v_permlane16_swap_b32_e32 v239, v241
	global_store_dwordx4 v[158:159], v[238:241], off
	ds_read_b128 v[62:65], v1 offset:128
	v_rcp_f32_e32 v72, v2
	v_add_f32_e32 v2, 1.0, v77
	v_pk_add_f32 v[44:45], v[44:45], 1.0 op_sel_hi:[1,0]
	v_rcp_f32_e32 v77, v2
	v_mul_f32_e32 v2, v44, v45
	v_rcp_f32_e32 v73, v2
	ds_read_b128 v[44:47], v1 offset:192
	s_waitcnt lgkmcnt(1)
	v_pk_mul_f32 v[58:59], v[64:65], v[58:59]
	v_pk_mul_f32 v[56:57], v[62:63], v[56:57]
	v_pk_mul_f32 v[58:59], v[72:73], v[58:59]
	v_pk_mul_f32 v[56:57], v[60:61], v[56:57]
	v_pk_fma_f32 v[58:59], v[76:77], v[66:67], v[58:59]
	v_pk_fma_f32 v[56:57], v[74:75], v[70:71], v[56:57]
	v_pk_mul_f32 v[42:43], v[0:1], v[42:43] op_sel_hi:[0,1]
	v_pk_mul_f32 v[0:1], v[0:1], v[40:41] op_sel_hi:[0,1]
	v_lshlrev_b32_e32 v40, 16, v54
	s_mov_b32 s100, s66
	v_lshl_add_u64 v[32:33], v[20:21], 0, s[100:101]
	global_load_dwordx4 v[32:35], v[32:33], off
	v_and_b32_e32 v41, 0xffff0000, v54
	v_cvt_pk_bf16_f32 v56, v56, v57
	v_cvt_pk_bf16_f32 v57, v58, v59
	v_lshlrev_b32_e32 v2, 16, v48
	v_and_b32_e32 v58, 0xffff0000, v48
	v_lshlrev_b32_e32 v59, 16, v49
	v_and_b32_e32 v60, 0xffff0000, v49
	v_lshlrev_b32_e32 v48, 16, v55
	v_and_b32_e32 v49, 0xffff0000, v55
	v_pk_mul_f32 v[54:55], v[40:41], v[40:41]
	v_mov_b64_e32 v[242:243], v[56:57]
	v_lshlrev_b32_e32 v56, 16, v50
	v_fmamk_f32 v54, v54, 0xbdd2d3e7, v93
	v_mul_f32_e32 v2, 0xbfb8aa3b, v2
	v_mul_f32_e32 v56, 0xbfb8aa3b, v56
	v_mul_f32_e32 v54, v54, v40
	v_and_b32_e32 v61, 0xffff0000, v50
	v_exp_f32_e32 v2, v2
	v_exp_f32_e32 v56, v56
	v_exp_f32_e32 v57, v54
	v_mul_f32_e32 v54, 0xbfb8aa3b, v58
	v_fmamk_f32 v55, v55, 0xbdd2d3e7, v93
	v_lshlrev_b32_e32 v62, 16, v51
	v_and_b32_e32 v63, 0xffff0000, v51
	v_pk_mul_f32 v[50:51], v[48:49], v[48:49]
	v_exp_f32_e32 v64, v54
	v_mul_f32_e32 v54, 0xbfb8aa3b, v61
	v_mul_f32_e32 v55, v55, v41
	v_exp_f32_e32 v54, v54
	v_exp_f32_e32 v55, v55
	v_mul_f32_e32 v58, 0xbfb8aa3b, v59
	v_fmamk_f32 v50, v50, 0xbdd2d3e7, v93
	v_exp_f32_e32 v65, v58
	v_mul_f32_e32 v58, 0xbfb8aa3b, v62
	v_mul_f32_e32 v50, v50, v48
	v_exp_f32_e32 v58, v58
	v_exp_f32_e32 v59, v50
	v_mul_f32_e32 v50, 0xbfb8aa3b, v60
	v_fmamk_f32 v51, v51, 0xbdd2d3e7, v93
	v_add_f32_e32 v2, 1.0, v2
	v_pk_add_f32 v[56:57], v[56:57], 1.0 op_sel_hi:[1,0]
	v_exp_f32_e32 v62, v50
	v_mul_f32_e32 v50, 0xbfb8aa3b, v63
	v_mul_f32_e32 v51, v51, v49
	v_rcp_f32_e32 v60, v2
	s_mov_b32 s100, 0x9f62000
	v_lshl_add_u64 v[20:21], v[20:21], 0, s[100:101]
	global_load_dwordx4 v[20:23], v[20:21], off offset:3072
	v_mul_f32_e32 v2, v56, v57
	v_exp_f32_e32 v50, v50
	v_exp_f32_e32 v51, v51
	v_rcp_f32_e32 v56, v2
	v_add_f32_e32 v2, 1.0, v64
	v_pk_add_f32 v[54:55], v[54:55], 1.0 op_sel_hi:[1,0]
	v_rcp_f32_e32 v61, v2
	v_mul_f32_e32 v2, v54, v55
	v_rcp_f32_e32 v57, v2
	v_add_f32_e32 v2, 1.0, v65
	v_pk_add_f32 v[58:59], v[58:59], 1.0 op_sel_hi:[1,0]
	v_rcp_f32_e32 v54, v2
	v_mul_f32_e32 v2, v58, v59
	v_rcp_f32_e32 v58, v2
	v_add_f32_e32 v2, 1.0, v62
	v_pk_add_f32 v[50:51], v[50:51], 1.0 op_sel_hi:[1,0]
	v_rcp_f32_e32 v55, v2
	v_mul_f32_e32 v2, v50, v51
	v_rcp_f32_e32 v59, v2
	s_waitcnt lgkmcnt(0)
	v_pk_mul_f32 v[46:47], v[46:47], v[48:49]
	v_pk_mul_f32 v[40:41], v[44:45], v[40:41]
	s_addk_i32 s38, 0x80
	v_pk_mul_f32 v[40:41], v[56:57], v[40:41]
	v_pk_mul_f32 v[44:45], v[58:59], v[46:47]
	v_pk_fma_f32 v[0:1], v[60:61], v[0:1], v[40:41]
	v_pk_fma_f32 v[42:43], v[54:55], v[42:43], v[44:45]
	v_cvt_pk_bf16_f32 v0, v0, v1
	v_cvt_pk_bf16_f32 v1, v42, v43
	v_mov_b64_e32 v[244:245], v[0:1]
	s_nop 1
	v_permlane16_swap_b32_e32 v242, v244
	v_permlane16_swap_b32_e32 v243, v245
	global_store_dwordx4 v[158:159], v[242:245], off offset:64
	s_waitcnt lgkmcnt(0)
	s_barrier
	s_add_u32 s54, s54, 0x160000
	s_addc_u32 s55, s55, 0
	s_cmp_eq_u32 s54, 0x1600000
	s_cbranch_scc1 .LBB0_281
